# attention loop: K/V/mask prefetch addresses from scalar bases + 32-bit lane offsets (no per-tile 64-bit VALU address math), next tile K/V written to LDS mid-tile
# speedup vs baseline: 1.0928x; 1.0007x over previous
; #define LAS __attribute__((address_space(3)))
; __device__ __forceinline__ void attn_unit(const AttArgs& a, int b, int h, int qb, LAS unsigned char* shm, int tid) {
;     const int lane = tid & 63, r32 = lane & 31, hi = lane >> 5, wave = __builtin_amdgcn_readfirstlane(tid >> 6); const int n = h >> 1;
;     const size_t rowb = (size_t)b * SEQ; const int q0 = qb * 256, NT = (q0 + 256) / 64;
;     const bf16* Qw = a.Q + (rowb + q0 + wave * 32) * 512 + h * 64;
;     const bf16* Kh = a.K + rowb * 256 + n * 64; const bf16* Vh = a.V + rowb * 256 + n * 64;
;     const bf16* ksrc = Kh + (size_t)lane * 256 + wave * 8;
;     const bf16* vsrc = Vh + (size_t)(16 * (wave & 3) + (lane >> 2)) * 256 + (wave >> 2) * 32 + (lane & 3) * 8;
;     const u64* mrow = a.MASK + (size_t)b * NT64 * SEQ + q0 + wave * 32 + r32;
;     LAS float* wsf = (LAS float*)(shm + AT_WS) + wave * 64;
;     bf16x8 qr[4];
; #pragma unroll
;     for (int d0 = 0; d0 < 4; ++d0) qr[d0] = *(const bf16x8*)(Qw + (size_t)r32 * 512 + d0 * 16 + hi * 8);
;     f32x16 o[2]; o[0] = f32x16{}; o[1] = f32x16{}; float m_run = 0.f, l_run = 0.f;
;     u32x4_t kr[2], vr[2]; u64 mwr[2];
;     kr[0] = *(const u32x4_t*)ksrc; vr[0] = *(const u32x4_t*)vsrc; mwr[0] = mrow[0];
;     kr[1] = *(const u32x4_t*)(ksrc + (size_t)64 * 256); vr[1] = *(const u32x4_t*)(vsrc + (size_t)64 * 256); mwr[1] = mrow[SEQ];
;     *(LAS u32x4_t*)(shm + AT_KV + wave * 1024 + lane * 16) = kr[0]; *(LAS u32x4_t*)(shm + AT_KV + 8192 + wave * 1024 + lane * 16) = vr[0];
;     __syncthreads();
;     for (int t2 = 0; t2 < NT; t2 += 2) {
; #pragma unroll
;       for (int par = 0; par < 2; ++par) { const int t = t2 + par;
;         LAS unsigned char* Kb = shm + AT_KV + par * 16384; LAS unsigned char* Vb = Kb + 8192; const u64 mw = mwr[par];
;         if (t + 2 < NT) { kr[par] = *(const u32x4_t*)(ksrc + (size_t)(t + 2) * 64 * 256); vr[par] = *(const u32x4_t*)(vsrc + (size_t)(t + 2) * 64 * 256); mwr[par] = mrow[(size_t)(t + 2) * SEQ]; }
;         f32x16 p0, p1;
;         { const unsigned nm0 = ~((unsigned)mw >> (4 * hi)), nm1 = ~((unsigned)(mw >> 32) >> (4 * hi)), nb = __float_as_uint(-m_run);
; #pragma unroll
;           for (int r = 0; r < 16; ++r) { const int bit = (r & 3) + 8 * (r >> 2); const unsigned t0 = (unsigned)__builtin_amdgcn_sbfe((int)nm0, bit, 1), t1 = (unsigned)__builtin_amdgcn_sbfe((int)nm1, bit, 1);
.LBB0_1065:
	v_readfirstlane_b32 s34, v99
	s_ashr_i32 s24, s34, 6
	s_and_b64 s[6:7], s[2:3], exec
	s_cselect_b32 s16, s11, s20
	s_lshl_b32 s14, s24, 5
	s_add_i32 s35, s16, 0x100
	s_or_b32 s6, s10, s16
	s_ashr_i32 s15, s14, 31
	s_add_u32 s6, s6, s14
	s_addc_u32 s7, 0, s15
	s_lshl_b32 s17, s24, 4
	v_and_or_b32 v3, s17, 48, v150
	s_ashr_i32 s17, s34, 3
	s_lshl_b32 s26, s24, 3
	s_and_b32 s28, s17, 0xffffffe0
	s_lshl_b64 s[18:19], s[6:7], 10
	s_ashr_i32 s27, s26, 31
	s_ashr_i32 s29, s28, 31
	s_lshl_b32 s36, s16, 3
	s_add_u32 s25, s21, s36
	s_addc_u32 s30, s22, 0
	s_lshl_b64 s[16:17], s[14:15], 3
	s_add_u32 s14, s25, s16
	v_lshlrev_b32_e32 v16, 9, v3
	v_mov_b32_e32 v17, v215
	s_addc_u32 s15, s30, s17
	s_lshl_b64 s[30:31], s[26:27], 1
	v_lshl_add_u64 v[6:7], s[0:1], 0, v[16:17]
	s_lshl_b64 s[28:29], s[28:29], 1
	v_lshl_add_u64 v[4:5], v[122:123], 0, s[30:31]
	v_lshl_add_u64 v[6:7], v[6:7], 0, s[28:29]
	v_mov_b32_e32 v113, v215
	v_lshl_add_u64 v[6:7], v[6:7], 0, v[112:113]
	global_load_dwordx4 v[82:85], v[4:5], off
	global_load_dwordx4 v[86:89], v[6:7], off
	v_lshl_add_u64 v[10:11], v[120:121], 0, s[18:19]
	v_add_co_u32_e32 v4, vcc, s33, v4
	global_load_dwordx4 v[66:69], v[10:11], off
	global_load_dwordx4 v[70:73], v[10:11], off offset:32
	global_load_dwordx4 v[74:77], v[10:11], off offset:64
	global_load_dwordx4 v[78:81], v[10:11], off offset:96
	v_addc_co_u32_e32 v5, vcc, 0, v5, vcc
	v_lshlrev_b32_e32 v2, 3, v98
	v_mov_b32_e32 v3, v215
	v_add_co_u32_e32 v6, vcc, s33, v6
	v_lshl_add_u64 v[8:9], s[14:15], 0, v[2:3]
	s_nop 0
	v_addc_co_u32_e32 v7, vcc, 0, v7, vcc
	v_add_co_u32_e32 v8, vcc, s33, v8
	s_and_b32 s18, s34, 0x3fffffc0
	s_nop 0
	v_addc_co_u32_e32 v9, vcc, 0, v9, vcc
	global_load_dwordx2 v[34:35], v2, s[14:15]
	global_load_dwordx2 v[140:141], v[8:9], off
	global_load_dwordx4 v[90:93], v[4:5], off
	global_load_dwordx4 v[94:97], v[6:7], off
	s_lshl_b32 s18, s18, 2
	s_lshr_b32 s26, s35, 6
	s_lshl_b32 s19, s24, 10
	s_add_i32 s18, s18, 0
	s_add_u32 s16, s16, s36
	v_mov_b32_e32 v119, 0
	v_lshl_add_u64 v[16:17], s[28:29], 0, v[16:17]
	s_addc_u32 s17, s17, 0
	s_mov_b32 s25, 3
	s_mov_b64 s[14:15], 0
	v_mov_b32_e32 v113, 0
	v_mov_b32_e32 v2, 0
	v_mov_b32_e32 v3, v119
	v_mov_b32_e32 v4, v119
	v_mov_b32_e32 v5, v119
	v_mov_b32_e32 v6, v119
	v_mov_b32_e32 v7, v119
	v_mov_b32_e32 v8, v119
	v_mov_b32_e32 v9, v119
	v_mov_b32_e32 v10, v119
	v_mov_b32_e32 v11, v119
	v_mov_b32_e32 v12, v119
	v_mov_b32_e32 v13, v119
	v_mov_b32_e32 v14, v119
	v_mov_b32_e32 v15, v119
	v_add_u32_e32 v117, s19, v151
	v_lshl_add_u64 v[132:133], v[126:127], 0, s[30:31]
	v_lshl_add_u64 v[134:135], v[128:129], 0, v[16:17]
	v_lshl_add_u32 v115, v98, 2, s18
	v_lshl_add_u32 v111, v152, 2, s18
	v_lshl_add_u64 v[136:137], v[130:131], 0, s[16:17]
	v_mov_b32_e32 v16, v119
	v_mov_b32_e32 v17, v119
	v_mov_b32_e32 v18, 0
	v_mov_b32_e32 v19, v119
	v_mov_b32_e32 v20, v119
	v_mov_b32_e32 v21, v119
	v_mov_b32_e32 v22, v119
	v_mov_b32_e32 v23, v119
	v_mov_b32_e32 v24, v119
	v_mov_b32_e32 v25, v119
	v_mov_b32_e32 v26, v119
	v_mov_b32_e32 v27, v119
	v_mov_b32_e32 v28, v119
	v_mov_b32_e32 v29, v119
	v_mov_b32_e32 v30, v119
	v_mov_b32_e32 v31, v119
	v_mov_b32_e32 v32, v119
	v_mov_b32_e32 v33, v119
	s_waitcnt vmcnt(9)
	ds_write_b128 v117, v[82:85]
	s_waitcnt vmcnt(8)
	ds_write_b128 v117, v[86:89] offset:8192
	s_waitcnt lgkmcnt(0)
	s_barrier
	s_waitcnt vmcnt(3)
	v_mov_b64_e32 v[138:139], v[34:35]
	v_xor_b32_e32 v177, 0x80000000, v113
	v_lshrrev_b32_e32 v50, v152, v35
	v_lshrrev_b32_e32 v34, v152, v34
	v_bfe_i32 v49, v34, 27, 1
	v_bfe_i32 v48, v34, 26, 1
	v_bfe_i32 v47, v34, 25, 1
	v_bfe_i32 v46, v34, 24, 1
	v_bfe_i32 v45, v34, 19, 1
	v_bfe_i32 v44, v34, 18, 1
	v_bfe_i32 v43, v34, 17, 1
	v_bfe_i32 v42, v34, 16, 1
	v_bfe_i32 v41, v34, 11, 1
	v_bfe_i32 v40, v34, 10, 1
	v_bfe_i32 v39, v34, 9, 1
	v_bfe_i32 v38, v34, 8, 1
	v_bfe_i32 v37, v34, 3, 1
	v_bfe_i32 v36, v34, 2, 1
	v_bfe_i32 v35, v34, 1, 1
	v_bfe_i32 v34, v34, 0, 1
	v_bfi_b32 v49, v49, v177, v245
	v_bfi_b32 v48, v48, v177, v245
	v_bfi_b32 v47, v47, v177, v245
	v_bfi_b32 v46, v46, v177, v245
	v_bfi_b32 v45, v45, v177, v245
	v_bfi_b32 v44, v44, v177, v245
	v_bfi_b32 v43, v43, v177, v245
	v_bfi_b32 v42, v42, v177, v245
	v_bfi_b32 v41, v41, v177, v245
	v_bfi_b32 v40, v40, v177, v245
	v_bfi_b32 v39, v39, v177, v245
	v_bfi_b32 v38, v38, v177, v245
	v_bfi_b32 v37, v37, v177, v245
	v_bfi_b32 v36, v36, v177, v245
	v_bfi_b32 v35, v35, v177, v245
	v_bfi_b32 v34, v34, v177, v245
	v_readfirstlane_b32 s46, v132
	v_readfirstlane_b32 s47, v133
	v_readfirstlane_b32 s48, v134
	v_readfirstlane_b32 s49, v135
	v_readfirstlane_b32 s50, v136
	v_readfirstlane_b32 s51, v137
	s_nop 3
	v_subrev_u32_e32 v146, s46, v132
	v_subrev_u32_e32 v144, s48, v134
	v_subrev_u32_e32 v142, s50, v136
	s_add_u32 s46, s46, 0x1df10000
	s_addc_u32 s47, s47, 0
	s_add_u32 s48, s48, 0x1e710000
	s_addc_u32 s49, s49, 0
	s_add_u32 s50, s50, 0x1c710000
	s_addc_u32 s51, s51, 0
.LBB0_1066:
	s_add_i32 s27, s25, -1
	s_cmp_lt_u32 s27, s26
	s_cselect_b64 s[16:17], -1, 0
	s_and_b64 vcc, exec, s[16:17]
	ds_read_b128 v[178:181], v176
	ds_read_b128 v[182:185], v176 offset:2048
	ds_read_b128 v[186:189], v176 offset:4096
	ds_read_b128 v[192:195], v176 offset:6144
	ds_read_b128 v[196:199], v176 offset:512
	ds_read_b128 v[200:203], v176 offset:2560
	ds_read_b128 v[204:207], v176 offset:4608
	ds_read_b128 v[208:211], v176 offset:6656
	s_cbranch_vccz .LBB0_1068
	global_load_dwordx4 v[82:85], v146, s[46:47]
	global_load_dwordx4 v[86:89], v144, s[48:49]
	global_load_dwordx2 v[138:139], v142, s[50:51]
	s_add_u32 s46, s46, 0x8000
	s_addc_u32 s47, s47, 0
	s_add_u32 s48, s48, 0x8000
	s_addc_u32 s49, s49, 0
	s_add_u32 s50, s50, 0x8000
	s_addc_u32 s51, s51, 0

; __device__ __forceinline__ void attn_unit(const AttArgs& a, int b, int h, int qb, LAS unsigned char* shm, int tid) {
;     ...
;           for (int r = 0; r < 16; ++r) { p0[r] = __builtin_amdgcn_exp2f(p0[r]); p1[r] = __builtin_amdgcn_exp2f(p1[r]); rs2 += (f32x2_t){p0[r], p1[r]}; }
;           rs = rs2[0] + rs2[1]; l_run += rs; }
;         const bool regrow = __any(rs > 1.0995e12f);
;         u32x4_t pw0, pw1, pw2, pw3;
;         pw0 = (u32x4_t){cvtpk(p0[0], p0[1]), cvtpk(p0[2], p0[3]), cvtpk(p0[4], p0[5]), cvtpk(p0[6], p0[7])}; pw1 = (u32x4_t){cvtpk(p0[8], p0[9]), cvtpk(p0[10], p0[11]), cvtpk(p0[12], p0[13]), cvtpk(p0[14], p0[15])};
;         pw2 = (u32x4_t){cvtpk(p1[0], p1[1]), cvtpk(p1[2], p1[3]), cvtpk(p1[4], p1[5]), cvtpk(p1[6], p1[7])}; pw3 = (u32x4_t){cvtpk(p1[8], p1[9]), cvtpk(p1[10], p1[11]), cvtpk(p1[12], p1[13]), cvtpk(p1[14], p1[15])};
;         { const unsigned vb = (unsigned)(uintptr_t)Vb + ((lane >> 4) & 1) * 32 + (lane & 3) * 8 + (4 * hi + ((lane & 15) >> 2)) * 64;
; #pragma unroll
;           for (int d0 = 0; d0 < 2; ++d0) { s16x4 lo[4], hh[4];
; #pragma unroll
;               for (int ks = 0; ks < 4; ++ks) {
;                   asm volatile("ds_read_b64_tr_b16 %0,%1 offset:%c2" : "=&v"(lo[ks]) : "v"(vb), "i"(d0 * 4096 + ks * 1024) : "memory");
;                   asm volatile("ds_read_b64_tr_b16 %0,%1 offset:%c2" : "=&v"(hh[ks]) : "v"(vb), "i"(d0 * 4096 + ks * 1024 + 512) : "memory"); }
;               asm volatile("s_waitcnt lgkmcnt(0)" ::: "memory"); __builtin_amdgcn_sched_barrier(0);
;     ...
;               o[d0] = __builtin_amdgcn_mfma_f32_32x32x16_bf16(__builtin_bit_cast(bf16x8, pw0), DSA_PK(0), o[d0], 0, 0, 0);
;               o[d0] = __builtin_amdgcn_mfma_f32_32x32x16_bf16(__builtin_bit_cast(bf16x8, pw1), DSA_PK(1), o[d0], 0, 0, 0);
;               o[d0] = __builtin_amdgcn_mfma_f32_32x32x16_bf16(__builtin_bit_cast(bf16x8, pw2), DSA_PK(2), o[d0], 0, 0, 0);
;               o[d0] = __builtin_amdgcn_mfma_f32_32x32x16_bf16(__builtin_bit_cast(bf16x8, pw3), DSA_PK(3), o[d0], 0, 0, 0);
;     ...
;           } }
;         if (regrow) { const float rsf = __builtin_amdgcn_fmed3f(rs, __shfl_xor(rs, 32), INFINITY); const float dl = rsf > 1.0995e12f ? floorf(__log2f(rsf)) : 0.f;
;             m_run += dl; const float alpha = __builtin_amdgcn_exp2f(-dl); l_run *= alpha;
;             if (hi == 0) wsf[r32] = alpha; asm volatile("s_waitcnt lgkmcnt(0)" ::: "memory");
.Latt_j0:
	v_cvt_pk_bf16_f32 v196, v34, v35
	v_pk_add_f32 v[212:213], v[34:35], v[36:37]
	v_cvt_pk_bf16_f32 v197, v36, v37
	v_pk_add_f32 v[212:213], v[38:39], v[212:213]
	v_cvt_pk_bf16_f32 v198, v38, v39
	v_pk_add_f32 v[212:213], v[40:41], v[212:213]
	v_cvt_pk_bf16_f32 v199, v40, v41
	v_pk_add_f32 v[212:213], v[42:43], v[212:213]
	v_cvt_pk_bf16_f32 v200, v42, v43
	v_pk_add_f32 v[212:213], v[44:45], v[212:213]
	v_cvt_pk_bf16_f32 v201, v44, v45
	v_pk_add_f32 v[212:213], v[46:47], v[212:213]
	v_cvt_pk_bf16_f32 v202, v46, v47
	v_pk_add_f32 v[212:213], v[48:49], v[212:213]
	v_cvt_pk_bf16_f32 v203, v48, v49
	s_waitcnt lgkmcnt(0)
	s_waitcnt vmcnt(3)
	ds_write_b128 v117, v[90:93] offset:16384
	ds_write_b128 v117, v[94:97] offset:24576
	v_mfma_f32_32x32x16_bf16 v[2:17], v[196:199], v[178:181], v[2:17]
	ds_read_b64_tr_b16 v[178:179],v153 offset:2048
	ds_read_b64_tr_b16 v[180:181],v153 offset:2560
	v_exp_f32_e32 v50, v50
	v_exp_f32_e32 v51, v51
	v_exp_f32_e32 v52, v52
	v_exp_f32_e32 v53, v53
	v_mfma_f32_32x32x16_bf16 v[18:33], v[196:199], v[182:185], v[18:33]
	ds_read_b64_tr_b16 v[182:183],v153 offset:6144
	ds_read_b64_tr_b16 v[184:185],v153 offset:6656
	v_exp_f32_e32 v54, v54
	v_exp_f32_e32 v55, v55
	v_exp_f32_e32 v56, v56
	v_exp_f32_e32 v57, v57
	v_mfma_f32_32x32x16_bf16 v[2:17], v[200:203], v[186:189], v[2:17]
	ds_read_b64_tr_b16 v[186:187],v153 offset:3072
	ds_read_b64_tr_b16 v[188:189],v153 offset:3584
	v_exp_f32_e32 v58, v58
	v_exp_f32_e32 v59, v59
	v_exp_f32_e32 v60, v60
	v_exp_f32_e32 v61, v61
	v_mfma_f32_32x32x16_bf16 v[18:33], v[200:203], v[192:195], v[18:33]
	ds_read_b64_tr_b16 v[192:193],v153 offset:7168
	ds_read_b64_tr_b16 v[194:195],v153 offset:7680
	v_exp_f32_e32 v62, v62
	v_exp_f32_e32 v63, v63
	v_exp_f32_e32 v64, v64
	v_exp_f32_e32 v65, v65
	v_cvt_pk_bf16_f32 v204, v50, v51
	v_cvt_pk_bf16_f32 v205, v52, v53
	v_cvt_pk_bf16_f32 v206, v54, v55
	v_cvt_pk_bf16_f32 v207, v56, v57
	v_cvt_pk_bf16_f32 v208, v58, v59
	v_cvt_pk_bf16_f32 v209, v60, v61
	v_cvt_pk_bf16_f32 v210, v62, v63
	v_cvt_pk_bf16_f32 v211, v64, v65
	v_pk_add_f32 v[212:213], v[50:51], v[212:213]
	v_pk_add_f32 v[212:213], v[52:53], v[212:213]
	v_pk_add_f32 v[212:213], v[54:55], v[212:213]
	v_pk_add_f32 v[212:213], v[56:57], v[212:213]
	v_pk_add_f32 v[212:213], v[58:59], v[212:213]
	v_pk_add_f32 v[212:213], v[60:61], v[212:213]
	v_pk_add_f32 v[212:213], v[62:63], v[212:213]
	v_pk_add_f32 v[212:213], v[64:65], v[212:213]
	v_add_f32_e32 v212, v212, v213
	v_cmp_lt_f32_e32 vcc, s61, v212
	v_add_f32_e32 v119, v119, v212
	s_waitcnt lgkmcnt(6)
	v_mfma_f32_32x32x16_bf16 v[2:17], v[204:207], v[178:181], v[2:17]
	v_lshrrev_b32_e32 v34, v152, v140
	v_xor_b32_e32 v177, 0x80000000, v113
	v_bfe_i32 v49, v34, 27, 1
	v_bfe_i32 v48, v34, 26, 1
	v_bfe_i32 v47, v34, 25, 1
	v_bfe_i32 v46, v34, 24, 1
	v_bfe_i32 v45, v34, 19, 1
	v_bfe_i32 v44, v34, 18, 1
	v_bfe_i32 v43, v34, 17, 1
	s_waitcnt lgkmcnt(4)
	v_mfma_f32_32x32x16_bf16 v[18:33], v[204:207], v[182:185], v[18:33]
	v_bfe_i32 v42, v34, 16, 1
	v_bfe_i32 v41, v34, 11, 1
	v_bfe_i32 v40, v34, 10, 1
	v_bfe_i32 v39, v34, 9, 1
	v_bfe_i32 v38, v34, 8, 1
	v_bfe_i32 v37, v34, 3, 1
	v_bfe_i32 v36, v34, 2, 1
	v_bfe_i32 v35, v34, 1, 1
	v_bfe_i32 v34, v34, 0, 1
	s_waitcnt lgkmcnt(2)
	v_mfma_f32_32x32x16_bf16 v[2:17], v[208:211], v[186:189], v[2:17]
	v_bfi_b32 v49, v49, v177, v245
	v_bfi_b32 v48, v48, v177, v245
	v_bfi_b32 v47, v47, v177, v245
	v_bfi_b32 v46, v46, v177, v245
	v_bfi_b32 v45, v45, v177, v245
	v_bfi_b32 v44, v44, v177, v245
	v_bfi_b32 v43, v43, v177, v245
	v_bfi_b32 v42, v42, v177, v245
	v_bfi_b32 v41, v41, v177, v245
	s_waitcnt lgkmcnt(0)
	v_mfma_f32_32x32x16_bf16 v[18:33], v[208:211], v[192:195], v[18:33]
	v_bfi_b32 v40, v40, v177, v245
	v_bfi_b32 v39, v39, v177, v245
	v_bfi_b32 v38, v38, v177, v245
	v_bfi_b32 v37, v37, v177, v245
	v_bfi_b32 v36, v36, v177, v245
	v_bfi_b32 v35, v35, v177, v245
	v_bfi_b32 v34, v34, v177, v245
	v_lshrrev_b32_e32 v50, v152, v141
	s_cbranch_vccz .LBB0_1074
	v_and_b32_e32 v192, 64, v240
	v_xor_b32_e32 v213, 32, v240
	v_add_u32_e32 v192, 64, v192
	v_cmp_lt_i32_e32 vcc, v213, v192
	s_nop 1
	v_cndmask_b32_e32 v213, v240, v213, vcc
	v_lshlrev_b32_e32 v213, 2, v213
	ds_bpermute_b32 v213, v213, v212
	v_max_f32_e32 v212, v212, v212
	s_waitcnt lgkmcnt(0)
	v_max_f32_e32 v213, v213, v213
	v_max_f32_e32 v212, v212, v213
	v_log_f32_e32 v213, v212
	v_cmp_lt_f32_e32 vcc, s61, v212
	v_floor_f32_e32 v213, v213
	s_nop 0
	v_cndmask_b32_e32 v212, 0, v213, vcc
	v_exp_f32_e64 v213, -v212
	s_and_saveexec_b64 s[18:19], s[12:13]
	ds_write_b32 v115, v213 offset:32768
	s_or_b64 exec, exec, s[18:19]
	s_waitcnt lgkmcnt(0)
	v_add_f32_e32 v113, v113, v212
	v_mul_f32_e32 v119, v119, v213
	ds_read_b128 v[192:195], v111 offset:32768
	ds_read_b128 v[196:199], v111 offset:32800
	ds_read_b128 v[200:203], v111 offset:32832
	ds_read_b128 v[204:207], v111 offset:32864
	v_xor_b32_e32 v177, 0x80000000, v113
	v_sub_f32_e32 v34, v34, v212
	v_sub_f32_e32 v35, v35, v212
	v_sub_f32_e32 v36, v36, v212
	v_sub_f32_e32 v37, v37, v212
	v_sub_f32_e32 v38, v38, v212
	v_sub_f32_e32 v39, v39, v212
	v_sub_f32_e32 v40, v40, v212
	v_sub_f32_e32 v41, v41, v212
	v_sub_f32_e32 v42, v42, v212
	v_sub_f32_e32 v43, v43, v212
	v_sub_f32_e32 v44, v44, v212
	v_sub_f32_e32 v45, v45, v212
	v_sub_f32_e32 v46, v46, v212
	v_sub_f32_e32 v47, v47, v212
	v_sub_f32_e32 v48, v48, v212
	v_sub_f32_e32 v49, v49, v212
	s_waitcnt lgkmcnt(3)
	v_pk_mul_f32 v[4:5], v[4:5], v[194:195]
	s_waitcnt lgkmcnt(2)
	v_pk_mul_f32 v[8:9], v[8:9], v[198:199]
	s_waitcnt lgkmcnt(1)
	v_pk_mul_f32 v[12:13], v[12:13], v[202:203]
	s_waitcnt lgkmcnt(0)
	v_pk_mul_f32 v[16:17], v[16:17], v[206:207]
	v_pk_mul_f32 v[14:15], v[14:15], v[204:205]
	v_pk_mul_f32 v[10:11], v[10:11], v[200:201]
	v_pk_mul_f32 v[6:7], v[6:7], v[196:197]
	v_pk_mul_f32 v[2:3], v[2:3], v[192:193]
	v_pk_mul_f32 v[32:33], v[32:33], v[206:207]
	v_pk_mul_f32 v[28:29], v[28:29], v[202:203]
	v_pk_mul_f32 v[24:25], v[24:25], v[198:199]
	v_pk_mul_f32 v[20:21], v[20:21], v[194:195]
	v_pk_mul_f32 v[30:31], v[30:31], v[204:205]
	v_pk_mul_f32 v[26:27], v[26:27], v[200:201]
	v_pk_mul_f32 v[22:23], v[22:23], v[196:197]
	v_pk_mul_f32 v[18:19], v[18:19], v[192:193]
; #define LAS __attribute__((address_space(3)))
; __device__ __forceinline__ void attn_unit(const AttArgs& a, int b, int h, int qb, LAS unsigned char* shm, int tid) {
;     ...
;         LAS unsigned char* Kb = shm + AT_KV + par * 16384; LAS unsigned char* Vb = Kb + 8192; const u64 mw = mwr[par];
;         if (t + 2 < NT) { kr[par] = *(const u32x4_t*)(ksrc + (size_t)(t + 2) * 64 * 256); vr[par] = *(const u32x4_t*)(vsrc + (size_t)(t + 2) * 64 * 256); mwr[par] = mrow[(size_t)(t + 2) * SEQ]; }
;         f32x16 p0, p1;
;         { const unsigned nm0 = ~((unsigned)mw >> (4 * hi)), nm1 = ~((unsigned)(mw >> 32) >> (4 * hi)), nb = __float_as_uint(-m_run);
; #pragma unroll
;           for (int r = 0; r < 16; ++r) { const int bit = (r & 3) + 8 * (r >> 2); const unsigned t0 = (unsigned)__builtin_amdgcn_sbfe((int)nm0, bit, 1), t1 = (unsigned)__builtin_amdgcn_sbfe((int)nm1, bit, 1);
;               p0[r] = __uint_as_float((t0 & 0xff800000u) | (~t0 & nb)); p1[r] = __uint_as_float((t1 & 0xff800000u) | (~t1 & nb)); } }
;         { LAS unsigned char* kb = Kb + hi * 1024 + r32 * 16;
; #pragma unroll
;           for (int d0 = 0; d0 < 4; ++d0) { const bf16x8 k0 = *(const LAS bf16x8*)(kb + d0 * 2048), k1 = *(const LAS bf16x8*)(kb + d0 * 2048 + 512);
;               p0 = __builtin_amdgcn_mfma_f32_32x32x16_bf16(k0, qr[d0], p0, 0, 0, 0); p1 = __builtin_amdgcn_mfma_f32_32x32x16_bf16(k1, qr[d0], p1, 0, 0, 0); } }
;         if (t == 0) {
;             float rm = __builtin_amdgcn_fmed3f(p0[0], p1[0], BIGF);
; #pragma unroll
;             for (int r = 1; r < 16; ++r) rm = __builtin_amdgcn_fmed3f(rm, __builtin_amdgcn_fmed3f(p0[r], p1[r], BIGF), BIGF);
;             const float rmf = __builtin_amdgcn_fmed3f(rm, __shfl_xor(rm, 32), BIGF); const float dl = (rmf == -INFINITY) ? 0.f : rmf;
;             m_run += dl;
; #pragma unroll
;             for (int r = 0; r < 16; ++r) { p0[r] -= dl; p1[r] -= dl; } }
;         float rs;
;         { typedef float f32x2_t __attribute__((ext_vector_type(2))); f32x2_t rs2 = {0.f, 0.f};
; #pragma unroll
;           for (int r = 0; r < 16; ++r) { p0[r] = __builtin_amdgcn_exp2f(p0[r]); p1[r] = __builtin_amdgcn_exp2f(p1[r]); rs2 += (f32x2_t){p0[r], p1[r]}; }
;     ...
;         if (t + 1 < NT) { LAS unsigned char* Kn = shm + AT_KV + (par ^ 1) * 16384; *(LAS u32x4_t*)(Kn + wave * 1024 + lane * 16) = kr[par ^ 1]; *(LAS u32x4_t*)(Kn + 8192 + wave * 1024 + lane * 16) = vr[par ^ 1]; }
.LBB0_1074:
.LBB0_1076:
	s_cmp_ge_u32 s25, s26
	v_mov_b64_e32 v[148:149], v[140:141]
	s_waitcnt lgkmcnt(0)
	s_barrier
	ds_read_b128 v[178:181], v176 offset:16384
	ds_read_b128 v[182:185], v176 offset:18432
	ds_read_b128 v[186:189], v176 offset:20480
	ds_read_b128 v[192:195], v176 offset:22528
	ds_read_b128 v[196:199], v176 offset:16896
	ds_read_b128 v[200:203], v176 offset:18944
	ds_read_b128 v[204:207], v176 offset:20992
	ds_read_b128 v[208:211], v176 offset:23040
	s_cbranch_scc1 .LBB0_1078
	global_load_dwordx4 v[90:93], v146, s[46:47]
	global_load_dwordx4 v[94:97], v144, s[48:49]
	global_load_dwordx2 v[148:149], v142, s[50:51]
	s_add_u32 s46, s46, 0x8000
	s_addc_u32 s47, s47, 0
	s_add_u32 s48, s48, 0x8000
	s_addc_u32 s49, s49, 0
	s_add_u32 s50, s50, 0x8000
	s_addc_u32 s51, s51, 0
.LBB0_1078:
	v_bfe_i32 v65, v50, 27, 1
	v_bfe_i32 v64, v50, 26, 1
	v_bfe_i32 v63, v50, 25, 1
	v_bfe_i32 v62, v50, 24, 1
	v_bfe_i32 v61, v50, 19, 1
	v_bfe_i32 v60, v50, 18, 1
	v_bfe_i32 v59, v50, 17, 1
	v_bfe_i32 v58, v50, 16, 1
	s_waitcnt lgkmcnt(7)
	v_mfma_f32_32x32x16_bf16 v[34:49], v[178:181], v[66:69], v[34:49]
	v_bfe_i32 v57, v50, 11, 1
	v_bfe_i32 v56, v50, 10, 1
	v_bfe_i32 v55, v50, 9, 1
	v_bfe_i32 v54, v50, 8, 1
	v_bfe_i32 v53, v50, 3, 1
	v_bfe_i32 v52, v50, 2, 1
	v_bfe_i32 v51, v50, 1, 1
	v_bfe_i32 v50, v50, 0, 1
	s_waitcnt lgkmcnt(6)
	v_mfma_f32_32x32x16_bf16 v[34:49], v[182:185], v[70:73], v[34:49]
	v_bfi_b32 v65, v65, v177, v245
	v_bfi_b32 v64, v64, v177, v245
	v_bfi_b32 v63, v63, v177, v245
	v_bfi_b32 v62, v62, v177, v245
	v_bfi_b32 v61, v61, v177, v245
	v_bfi_b32 v60, v60, v177, v245
	v_bfi_b32 v59, v59, v177, v245
	v_bfi_b32 v58, v58, v177, v245
	s_waitcnt lgkmcnt(5)
	v_mfma_f32_32x32x16_bf16 v[34:49], v[186:189], v[74:77], v[34:49]
	v_bfi_b32 v57, v57, v177, v245
	v_bfi_b32 v56, v56, v177, v245
	v_bfi_b32 v55, v55, v177, v245
	v_bfi_b32 v54, v54, v177, v245
	v_bfi_b32 v53, v53, v177, v245
	v_bfi_b32 v52, v52, v177, v245
	v_bfi_b32 v51, v51, v177, v245
	v_bfi_b32 v50, v50, v177, v245
	s_waitcnt lgkmcnt(4)
	v_mfma_f32_32x32x16_bf16 v[34:49], v[192:195], v[78:81], v[34:49]
	ds_read_b64_tr_b16 v[178:179],v154 offset:0
	ds_read_b64_tr_b16 v[180:181],v154 offset:512
	ds_read_b64_tr_b16 v[182:183],v154 offset:4096
	ds_read_b64_tr_b16 v[184:185],v154 offset:4608
	ds_read_b64_tr_b16 v[186:187],v154 offset:1024
	ds_read_b64_tr_b16 v[188:189],v154 offset:1536
	ds_read_b64_tr_b16 v[192:193],v154 offset:5120
	ds_read_b64_tr_b16 v[194:195],v154 offset:5632
	s_waitcnt lgkmcnt(11)
	v_mfma_f32_32x32x16_bf16 v[50:65], v[196:199], v[66:69], v[50:65]
	s_nop 3
	v_exp_f32_e32 v34, v34
	v_exp_f32_e32 v35, v35
	v_exp_f32_e32 v36, v36
	v_exp_f32_e32 v37, v37
	s_waitcnt lgkmcnt(10)
	v_mfma_f32_32x32x16_bf16 v[50:65], v[200:203], v[70:73], v[50:65]
	v_exp_f32_e32 v38, v38
	v_exp_f32_e32 v39, v39
	v_exp_f32_e32 v40, v40
	v_exp_f32_e32 v41, v41
	s_waitcnt lgkmcnt(9)
	v_mfma_f32_32x32x16_bf16 v[50:65], v[204:207], v[74:77], v[50:65]
	v_exp_f32_e32 v42, v42
	v_exp_f32_e32 v43, v43
	v_exp_f32_e32 v44, v44
	v_exp_f32_e32 v45, v45
	s_waitcnt lgkmcnt(8)
	v_mfma_f32_32x32x16_bf16 v[50:65], v[208:211], v[78:81], v[50:65]
	v_exp_f32_e32 v46, v46
	v_exp_f32_e32 v47, v47
	v_exp_f32_e32 v48, v48
	v_exp_f32_e32 v49, v49
	v_cvt_pk_bf16_f32 v196, v34, v35
	v_pk_add_f32 v[212:213], v[34:35], v[36:37]
	v_cvt_pk_bf16_f32 v197, v36, v37
	v_pk_add_f32 v[212:213], v[38:39], v[212:213]
	v_cvt_pk_bf16_f32 v198, v38, v39
	v_pk_add_f32 v[212:213], v[40:41], v[212:213]
	v_cvt_pk_bf16_f32 v199, v40, v41
	v_pk_add_f32 v[212:213], v[42:43], v[212:213]
	v_cvt_pk_bf16_f32 v200, v42, v43
	v_pk_add_f32 v[212:213], v[44:45], v[212:213]
	v_cvt_pk_bf16_f32 v201, v44, v45
	v_pk_add_f32 v[212:213], v[46:47], v[212:213]
	v_cvt_pk_bf16_f32 v202, v46, v47
	v_pk_add_f32 v[212:213], v[48:49], v[212:213]
	v_cvt_pk_bf16_f32 v203, v48, v49
	s_waitcnt lgkmcnt(0)
	s_andn2_b64 vcc, exec, s[16:17]
	s_cbranch_vccnz .Latt_nw1
	s_waitcnt vmcnt(3)
	ds_write_b128 v117, v[82:85]
	ds_write_b128 v117, v[86:89] offset:8192
; __device__ __forceinline__ void attn_unit(const AttArgs& a, int b, int h, int qb, LAS unsigned char* shm, int tid) {
;     ...
;           for (int r = 0; r < 16; ++r) { p0[r] = __builtin_amdgcn_exp2f(p0[r]); p1[r] = __builtin_amdgcn_exp2f(p1[r]); rs2 += (f32x2_t){p0[r], p1[r]}; }
;           rs = rs2[0] + rs2[1]; l_run += rs; }
;         const bool regrow = __any(rs > 1.0995e12f);
;         u32x4_t pw0, pw1, pw2, pw3;
;         pw0 = (u32x4_t){cvtpk(p0[0], p0[1]), cvtpk(p0[2], p0[3]), cvtpk(p0[4], p0[5]), cvtpk(p0[6], p0[7])}; pw1 = (u32x4_t){cvtpk(p0[8], p0[9]), cvtpk(p0[10], p0[11]), cvtpk(p0[12], p0[13]), cvtpk(p0[14], p0[15])};
;         pw2 = (u32x4_t){cvtpk(p1[0], p1[1]), cvtpk(p1[2], p1[3]), cvtpk(p1[4], p1[5]), cvtpk(p1[6], p1[7])}; pw3 = (u32x4_t){cvtpk(p1[8], p1[9]), cvtpk(p1[10], p1[11]), cvtpk(p1[12], p1[13]), cvtpk(p1[14], p1[15])};
;         { const unsigned vb = (unsigned)(uintptr_t)Vb + ((lane >> 4) & 1) * 32 + (lane & 3) * 8 + (4 * hi + ((lane & 15) >> 2)) * 64;
; #pragma unroll
;           for (int d0 = 0; d0 < 2; ++d0) { s16x4 lo[4], hh[4];
; #pragma unroll
;               for (int ks = 0; ks < 4; ++ks) {
;                   asm volatile("ds_read_b64_tr_b16 %0,%1 offset:%c2" : "=&v"(lo[ks]) : "v"(vb), "i"(d0 * 4096 + ks * 1024) : "memory");
;                   asm volatile("ds_read_b64_tr_b16 %0,%1 offset:%c2" : "=&v"(hh[ks]) : "v"(vb), "i"(d0 * 4096 + ks * 1024 + 512) : "memory"); }
;               asm volatile("s_waitcnt lgkmcnt(0)" ::: "memory"); __builtin_amdgcn_sched_barrier(0);
;     ...
;               o[d0] = __builtin_amdgcn_mfma_f32_32x32x16_bf16(__builtin_bit_cast(bf16x8, pw0), DSA_PK(0), o[d0], 0, 0, 0);
;               o[d0] = __builtin_amdgcn_mfma_f32_32x32x16_bf16(__builtin_bit_cast(bf16x8, pw1), DSA_PK(1), o[d0], 0, 0, 0);
;               o[d0] = __builtin_amdgcn_mfma_f32_32x32x16_bf16(__builtin_bit_cast(bf16x8, pw2), DSA_PK(2), o[d0], 0, 0, 0);
;               o[d0] = __builtin_amdgcn_mfma_f32_32x32x16_bf16(__builtin_bit_cast(bf16x8, pw3), DSA_PK(3), o[d0], 0, 0, 0);
;     ...
;           } }
;         if (regrow) { const float rsf = __builtin_amdgcn_fmed3f(rs, __shfl_xor(rs, 32), INFINITY); const float dl = rsf > 1.0995e12f ? floorf(__log2f(rsf)) : 0.f;
;             m_run += dl; const float alpha = __builtin_amdgcn_exp2f(-dl); l_run *= alpha;
;             if (hi == 0) wsf[r32] = alpha; asm volatile("s_waitcnt lgkmcnt(0)" ::: "memory");
.Latt_nw1:
	v_mfma_f32_32x32x16_bf16 v[2:17], v[196:199], v[178:181], v[2:17]
	ds_read_b64_tr_b16 v[178:179],v154 offset:2048
	ds_read_b64_tr_b16 v[180:181],v154 offset:2560
	v_exp_f32_e32 v50, v50
	v_exp_f32_e32 v51, v51
	v_exp_f32_e32 v52, v52
	v_exp_f32_e32 v53, v53
	v_mfma_f32_32x32x16_bf16 v[18:33], v[196:199], v[182:185], v[18:33]
	ds_read_b64_tr_b16 v[182:183],v154 offset:6144
	ds_read_b64_tr_b16 v[184:185],v154 offset:6656
	v_exp_f32_e32 v54, v54
	v_exp_f32_e32 v55, v55
	v_exp_f32_e32 v56, v56
	v_exp_f32_e32 v57, v57
	v_mfma_f32_32x32x16_bf16 v[2:17], v[200:203], v[186:189], v[2:17]
	ds_read_b64_tr_b16 v[186:187],v154 offset:3072
	ds_read_b64_tr_b16 v[188:189],v154 offset:3584
	v_exp_f32_e32 v58, v58
	v_exp_f32_e32 v59, v59
	v_exp_f32_e32 v60, v60
	v_exp_f32_e32 v61, v61
	v_mfma_f32_32x32x16_bf16 v[18:33], v[200:203], v[192:195], v[18:33]
	ds_read_b64_tr_b16 v[192:193],v154 offset:7168
	ds_read_b64_tr_b16 v[194:195],v154 offset:7680
	v_exp_f32_e32 v62, v62
	v_exp_f32_e32 v63, v63
	v_exp_f32_e32 v64, v64
	v_exp_f32_e32 v65, v65
	v_cvt_pk_bf16_f32 v204, v50, v51
	v_cvt_pk_bf16_f32 v205, v52, v53
	v_cvt_pk_bf16_f32 v206, v54, v55
	v_cvt_pk_bf16_f32 v207, v56, v57
	v_cvt_pk_bf16_f32 v208, v58, v59
	v_cvt_pk_bf16_f32 v209, v60, v61
	v_cvt_pk_bf16_f32 v210, v62, v63
	v_cvt_pk_bf16_f32 v211, v64, v65
	v_pk_add_f32 v[212:213], v[50:51], v[212:213]
	v_pk_add_f32 v[212:213], v[52:53], v[212:213]
	v_pk_add_f32 v[212:213], v[54:55], v[212:213]
	v_pk_add_f32 v[212:213], v[56:57], v[212:213]
	v_pk_add_f32 v[212:213], v[58:59], v[212:213]
	v_pk_add_f32 v[212:213], v[60:61], v[212:213]
	v_pk_add_f32 v[212:213], v[62:63], v[212:213]
	v_pk_add_f32 v[212:213], v[64:65], v[212:213]
	v_add_f32_e32 v212, v212, v213
	v_cmp_lt_f32_e32 vcc, s61, v212
	v_add_f32_e32 v119, v119, v212
	s_waitcnt lgkmcnt(6)
	v_mfma_f32_32x32x16_bf16 v[2:17], v[204:207], v[178:181], v[2:17]
	v_lshrrev_b32_e32 v34, v152, v138
	v_xor_b32_e32 v177, 0x80000000, v113
	v_bfe_i32 v49, v34, 27, 1
	v_bfe_i32 v48, v34, 26, 1
	v_bfe_i32 v47, v34, 25, 1
	v_bfe_i32 v46, v34, 24, 1
	v_bfe_i32 v45, v34, 19, 1
	v_bfe_i32 v44, v34, 18, 1
	v_bfe_i32 v43, v34, 17, 1
	s_waitcnt lgkmcnt(4)
	v_mfma_f32_32x32x16_bf16 v[18:33], v[204:207], v[182:185], v[18:33]
	v_bfe_i32 v42, v34, 16, 1
	v_bfe_i32 v41, v34, 11, 1
	v_bfe_i32 v40, v34, 10, 1
	v_bfe_i32 v39, v34, 9, 1
	v_bfe_i32 v38, v34, 8, 1
	v_bfe_i32 v37, v34, 3, 1
	v_bfe_i32 v36, v34, 2, 1
	v_bfe_i32 v35, v34, 1, 1
	v_bfe_i32 v34, v34, 0, 1
	s_waitcnt lgkmcnt(2)
	v_mfma_f32_32x32x16_bf16 v[2:17], v[208:211], v[186:189], v[2:17]
	v_bfi_b32 v49, v49, v177, v245
	v_bfi_b32 v48, v48, v177, v245
	v_bfi_b32 v47, v47, v177, v245
	v_bfi_b32 v46, v46, v177, v245
	v_bfi_b32 v45, v45, v177, v245
	v_bfi_b32 v44, v44, v177, v245
	v_bfi_b32 v43, v43, v177, v245
	v_bfi_b32 v42, v42, v177, v245
	v_bfi_b32 v41, v41, v177, v245
	s_waitcnt lgkmcnt(0)
	v_mfma_f32_32x32x16_bf16 v[18:33], v[208:211], v[192:195], v[18:33]
	v_bfi_b32 v40, v40, v177, v245
	v_bfi_b32 v39, v39, v177, v245
	v_bfi_b32 v38, v38, v177, v245
	v_bfi_b32 v37, v37, v177, v245
	v_bfi_b32 v36, v36, v177, v245
	v_bfi_b32 v35, v35, v177, v245
	v_bfi_b32 v34, v34, v177, v245
	v_lshrrev_b32_e32 v50, v152, v139
	s_cbranch_vccz .LBB0_1082
	v_and_b32_e32 v192, 64, v240
	v_xor_b32_e32 v213, 32, v240
	v_add_u32_e32 v192, 64, v192
	v_cmp_lt_i32_e32 vcc, v213, v192
	s_nop 1
	v_cndmask_b32_e32 v213, v240, v213, vcc
	v_lshlrev_b32_e32 v213, 2, v213
	ds_bpermute_b32 v213, v213, v212
	v_max_f32_e32 v212, v212, v212
	s_waitcnt lgkmcnt(0)
	v_max_f32_e32 v213, v213, v213
	v_max_f32_e32 v212, v212, v213
	v_log_f32_e32 v213, v212
	v_cmp_lt_f32_e32 vcc, s61, v212
	v_floor_f32_e32 v213, v213
	s_nop 0
	v_cndmask_b32_e32 v212, 0, v213, vcc
	v_exp_f32_e64 v213, -v212
	s_and_saveexec_b64 s[18:19], s[12:13]
	ds_write_b32 v115, v213 offset:32768
	s_or_b64 exec, exec, s[18:19]
	s_waitcnt lgkmcnt(0)
	v_add_f32_e32 v113, v113, v212
	v_mul_f32_e32 v119, v119, v213
	ds_read_b128 v[192:195], v111 offset:32768
	ds_read_b128 v[196:199], v111 offset:32800
	ds_read_b128 v[200:203], v111 offset:32832
	ds_read_b128 v[204:207], v111 offset:32864
	v_xor_b32_e32 v177, 0x80000000, v113
	v_sub_f32_e32 v34, v34, v212
	v_sub_f32_e32 v35, v35, v212
	v_sub_f32_e32 v36, v36, v212
	v_sub_f32_e32 v37, v37, v212
	v_sub_f32_e32 v38, v38, v212
	v_sub_f32_e32 v39, v39, v212
	v_sub_f32_e32 v40, v40, v212
	v_sub_f32_e32 v41, v41, v212
	v_sub_f32_e32 v42, v42, v212
	v_sub_f32_e32 v43, v43, v212
	v_sub_f32_e32 v44, v44, v212
	v_sub_f32_e32 v45, v45, v212
	v_sub_f32_e32 v46, v46, v212
	v_sub_f32_e32 v47, v47, v212
	v_sub_f32_e32 v48, v48, v212
	v_sub_f32_e32 v49, v49, v212
	s_waitcnt lgkmcnt(3)
	v_pk_mul_f32 v[4:5], v[4:5], v[194:195]
	s_waitcnt lgkmcnt(2)
	v_pk_mul_f32 v[8:9], v[8:9], v[198:199]
	s_waitcnt lgkmcnt(1)
	v_pk_mul_f32 v[12:13], v[12:13], v[202:203]
	s_waitcnt lgkmcnt(0)
	v_pk_mul_f32 v[16:17], v[16:17], v[206:207]
	v_pk_mul_f32 v[14:15], v[14:15], v[204:205]
	v_pk_mul_f32 v[10:11], v[10:11], v[200:201]
	v_pk_mul_f32 v[6:7], v[6:7], v[196:197]
	v_pk_mul_f32 v[2:3], v[2:3], v[192:193]
	v_pk_mul_f32 v[32:33], v[32:33], v[206:207]
	v_pk_mul_f32 v[28:29], v[28:29], v[202:203]
	v_pk_mul_f32 v[24:25], v[24:25], v[198:199]
	v_pk_mul_f32 v[20:21], v[20:21], v[194:195]
	v_pk_mul_f32 v[30:31], v[30:31], v[204:205]
	v_pk_mul_f32 v[26:27], v[26:27], v[200:201]
	v_pk_mul_f32 v[22:23], v[22:23], v[196:197]
	v_pk_mul_f32 v[18:19], v[18:19], v[192:193]
.LBB0_1082:
.LBB0_1084:
	s_add_u32 s14, s14, 0x10000
	s_addc_u32 s15, s15, 0
	s_add_i32 s25, s25, 2
	s_cmp_ge_u32 s27, s26
	s_waitcnt lgkmcnt(0)
	s_barrier
	s_cbranch_scc1 .LBB0_1086
	s_waitcnt vmcnt(0)
	v_mov_b64_e32 v[140:141], v[148:149]
	s_branch .LBB0_1066
